# the three grid syncs between GLU / out-proj / gate-up / down only collect the 32 workgroups that share the row panels (per-group counters; global counter still counted)
# speedup vs baseline: 1.0147x; 1.0147x over previous
; __device__ __forceinline__ CArgs* get_args() { CArgs* p = (CArgs*)__builtin_amdgcn_kernarg_segment_ptr(); asm volatile("" : "+s"(p)); return p; }
; __global__ void __launch_bounds__(512, 2) hymba_fwd(Args A_unused) {
;     ...
;     const int wave0 = __builtin_amdgcn_readfirstlane(threadIdx.x >> 6);
;     ...
;     unsigned nsync = 0;
;     ...
;     { PHASE_IDS(); if (blk == 0 && tid == 0) __hip_atomic_store((unsigned*)(get_args()->ws + WS_CTL), 0u, __ATOMIC_RELAXED, __HIP_MEMORY_SCOPE_AGENT);
_Z9hymba_fwd4Args:
	s_load_dword s67, s[0:1], 0xe0
	s_mov_b64 s[68:69], s[0:1]
	v_and_b32_e32 v1, 0x3ff, v0
	s_add_u32 s6, s68, 0xe0
	v_readfirstlane_b32 s24, v1
	s_addc_u32 s7, s69, 0
	s_lshr_b32 s77, s24, 6
	s_mov_b32 s76, s2
	s_mov_b32 s0, s77
	v_mbcnt_lo_u32_b32 v2, -1, 0
	v_mbcnt_hi_u32_b32 v2, -1, v2
	s_waitcnt lgkmcnt(0)
	s_mov_b32 s2, s67
	v_lshl_add_u32 v3, s0, 6, v2
	s_mov_b32 s4, s76
	s_nop 0
	v_or_b32_e32 v2, s4, v3
	v_readfirstlane_b32 s3, v3
	v_cmp_eq_u32_e32 vcc, 0, v2
	s_and_saveexec_b64 s[0:1], vcc
	s_cbranch_execz .LBB0_2
	s_mov_b64 s[8:9], s[68:69]
	s_load_dwordx2 s[8:9], s[8:9], 0xd8
	v_mov_b32_e32 v2, 0
	s_waitcnt lgkmcnt(0)
	global_store_dword v2, v2, s[8:9] sc1
	global_store_dword v2, v2, s[8:9] offset:256 sc1
	global_store_dword v2, v2, s[8:9] offset:320 sc1
	global_store_dword v2, v2, s[8:9] offset:384 sc1
	global_store_dword v2, v2, s[8:9] offset:448 sc1
	global_store_dword v2, v2, s[8:9] offset:512 sc1
	global_store_dword v2, v2, s[8:9] offset:576 sc1
	global_store_dword v2, v2, s[8:9] offset:640 sc1
	global_store_dword v2, v2, s[8:9] offset:704 sc1

; __device__ __forceinline__ CArgs* get_args() { CArgs* p = (CArgs*)__builtin_amdgcn_kernarg_segment_ptr(); asm volatile("" : "+s"(p)); return p; }
; #define GRID_SYNC() do { asm volatile("s_waitcnt vmcnt(0) lgkmcnt(0)" ::: "memory"); grid.sync(); \
;     asm volatile("buffer_inv sc1\n\ts_waitcnt vmcnt(0) lgkmcnt(0)" ::: "memory"); } while (0)
; __global__ void __launch_bounds__(512, 2) hymba_fwd(Args A_unused) {
;     ...
;     unsigned nsync = 0;
;     ...
;     { PHASE_IDS(); if (blk == 0 && tid == 0) __hip_atomic_store((unsigned*)(get_args()->ws + WS_CTL), 0u, __ATOMIC_RELAXED, __HIP_MEMORY_SCOPE_AGENT);
;       prologue(lds, wave, lane, gw, NGW); }
;     GRID_SYNC();
; #pragma nounroll
;     for (int l = 0; l < DEPTH; ++l) {
.LBB0_346:
	s_or_b64 exec, exec, s[0:1]
	s_mov_b32 s0, 0
	s_mov_b32 s73, 0
	v_writelane_b32 v254, s0, 0
	v_writelane_b32 v254, s0, 1
	v_writelane_b32 v254, s0, 60
	s_mov_b64 s[0:1], 0x80
	v_writelane_b32 v254, s0, 2
	s_barrier
	s_nop 0
	v_writelane_b32 v254, s1, 3
	s_mov_b32 s0, s73
	v_writelane_b32 v254, s0, 4
	buffer_inv sc1
	s_waitcnt vmcnt(0) lgkmcnt(0)
	s_cmp_lt_u32 s24, 64
	s_mov_b32 s74, s73
	v_writelane_b32 v254, s1, 5
	v_writelane_b32 v254, s68, 6
	s_mov_b32 s75, s73
	v_mbcnt_hi_u32_b32 v170, -1, v166
	v_writelane_b32 v254, s69, 7
	v_writelane_b32 v254, s67, 8
	v_writelane_b32 v254, s76, 9
	s_cselect_b64 s[92:93], -1, 0
	s_mov_b32 s72, s73
	v_mov_b64_e32 v[226:227], s[74:75]
	v_and_b32_e32 v177, 64, v170
	v_writelane_b32 v254, s77, 10
	s_mov_b64 s[70:71], 0x80
	s_mov_b64 s[80:81], 0x2aa00000
	s_mov_b64 s[82:83], 0x2a200000
	s_mov_b64 s[86:87], 0
	s_movk_i32 s84, 0x79
	v_mov_b32_e32 v145, 0
	v_mov_b32_e32 v167, 0x358637bd
	s_mov_b32 s33, 0x800000
	s_mov_b64 s[94:95], 0x80000
	s_movk_i32 s78, 0x200
	s_mov_b64 s[96:97], 0x1ba00000
	s_movk_i32 s79, 0x1e00
	v_mov_b32_e32 v168, 0xb9500d01
	v_mov_b32_e32 v169, 0xbab60b61
	s_movk_i32 s85, 0x1ff
	v_mov_b64_e32 v[224:225], s[72:73]
	s_mov_b32 s74, 0xf149f2ca
	v_mov_b32_e32 v173, 0x1000
	v_mov_b32_e32 v174, 0x2000
	v_mov_b32_e32 v175, 0x4000
	v_mov_b32_e32 v176, 0x8000
	s_movk_i32 s75, 0x3fe
	s_movk_i32 s90, 0x2c00
	v_xor_b32_e32 v172, 1, v170
	v_add_u32_e32 v171, 64, v177
	v_mov_b32_e32 v178, 1
	v_mov_b32_e32 v179, 0x7f800000
	v_mov_b32_e32 v180, 0x1e00
	v_mov_b32_e32 v181, 0x3ff
	v_mov_b32_e32 v182, 0xf149f2ca
	v_mov_b32_e32 v183, 0x80
	v_mov_b32_e32 v184, 0x100
	v_mov_b32_e32 v185, 0x200
	v_mov_b32_e32 v186, 0x400
	v_mov_b32_e32 v187, 0x800
	v_mov_b64_e32 v[146:147], 0x200
	v_mov_b64_e32 v[148:149], 0x1ff
	v_writelane_b32 v254, s92, 11
	s_nop 1
	v_writelane_b32 v254, s93, 12
	s_branch .LBB0_348

.LBB0_1325:
	s_or_b64 exec, exec, s[6:7]
	s_and_b32 s4, s76, 7
	s_lshl_b32 s4, s4, 6
	s_add_i32 s4, s4, 0x100
	s_add_u32 s2, s2, s4
	s_addc_u32 s3, s3, 0
	global_atomic_add v145, v0, s[2:3]
	v_readlane_b32 s6, v254, 60
	s_add_i32 s6, s6, 1
	s_nop 0
	v_writelane_b32 v254, s6, 60
	s_lshr_b32 s4, s67, 3
	s_mul_i32 s6, s6, s4
	s_mov_b32 s7, 0x400000
	s_branch .LBB0_1327
